# SGU LayerNorm statistics pass: 16 loads in flight per wave instead of one load per wait
# speedup vs baseline: 1.0175x; 1.0090x over previous
; __device__ __forceinline__ void unpack8(const u32x4 w, float* v) { v[0] = bflo(w.x); v[1] = bfhi(w.x); v[2] = bflo(w.y); v[3] = bfhi(w.y); v[4] = bflo(w.z); v[5] = bfhi(w.z); v[6] = bflo(w.w); v[7] = bfhi(w.w); }
; __device__ __forceinline__ void sgu_unit(const bf16_t* __restrict__ VCT, const bf16_t* __restrict__ U, const bf16_t* __restrict__ GC, bf16_t* __restrict__ OC, ...
;     ...
;         const int tl = lane & 15, cq = lane >> 4;
;         const bf16_t* p = VCT + (size_t)(w * 128 + cq) * PT + tok0 + 8 * tl;
;         float sm[8], sq[8];
; #pragma unroll
;         for (int e = 0; e < 8; ++e) { sm[e] = 0.f; sq[e] = 0.f; }
; #pragma unroll 8
;         for (int c4 = 0; c4 < 32; ++c4) { float v[8]; unpack8(*(const u32x4*)(p + (size_t)(c4 * 4) * PT), v);
; #pragma unroll
;             for (int e = 0; e < 8; ++e) { sm[e] += v[e]; sq[e] += v[e] * v[e]; } }
.LBB0_222:
	v_lshl_add_u64 v[22:23], v[0:1], 0, s[8:9]
	s_mov_b32 s98, 0x39600000
	s_mov_b32 s99, 0
	v_lshl_add_u64 v[18:19], v[22:23], 0, s[98:99]
	s_mov_b32 s98, 0x20200
	global_load_dwordx4 v[36:39], v[18:19], off
	v_lshl_add_u64 v[20:21], v[18:19], 0, s[98:99]
	global_load_dwordx4 v[40:43], v[20:21], off
	v_lshl_add_u64 v[18:19], v[20:21], 0, s[98:99]
	global_load_dwordx4 v[44:47], v[18:19], off
	v_lshl_add_u64 v[20:21], v[18:19], 0, s[98:99]
	global_load_dwordx4 v[48:51], v[20:21], off
	v_lshl_add_u64 v[18:19], v[20:21], 0, s[98:99]
	global_load_dwordx4 v[52:55], v[18:19], off
	v_lshl_add_u64 v[20:21], v[18:19], 0, s[98:99]
	global_load_dwordx4 v[56:59], v[20:21], off
	v_lshl_add_u64 v[18:19], v[20:21], 0, s[98:99]
	global_load_dwordx4 v[60:63], v[18:19], off
	v_lshl_add_u64 v[20:21], v[18:19], 0, s[98:99]
	global_load_dwordx4 v[64:67], v[20:21], off
	v_lshl_add_u64 v[18:19], v[20:21], 0, s[98:99]
	global_load_dwordx4 v[68:71], v[18:19], off
	v_lshl_add_u64 v[20:21], v[18:19], 0, s[98:99]
	global_load_dwordx4 v[72:75], v[20:21], off
	v_lshl_add_u64 v[18:19], v[20:21], 0, s[98:99]
	global_load_dwordx4 v[76:79], v[18:19], off
	v_lshl_add_u64 v[20:21], v[18:19], 0, s[98:99]
	global_load_dwordx4 v[80:83], v[20:21], off
	v_lshl_add_u64 v[18:19], v[20:21], 0, s[98:99]
	global_load_dwordx4 v[84:87], v[18:19], off
	v_lshl_add_u64 v[20:21], v[18:19], 0, s[98:99]
	global_load_dwordx4 v[88:91], v[20:21], off
	v_lshl_add_u64 v[18:19], v[20:21], 0, s[98:99]
	global_load_dwordx4 v[92:95], v[18:19], off
	v_lshl_add_u64 v[20:21], v[18:19], 0, s[98:99]
	global_load_dwordx4 v[96:99], v[20:21], off
	s_waitcnt vmcnt(15)
	v_lshlrev_b32_e32 v24, 16, v36
	v_and_b32_e32 v26, 0xffff0000, v36
	v_lshlrev_b32_e32 v28, 16, v37
	v_and_b32_e32 v30, 0xffff0000, v37
	v_lshlrev_b32_e32 v32, 16, v38
	v_and_b32_e32 v34, 0xffff0000, v38
	v_mul_f32_e32 v25, v24, v24
	v_mul_f32_e32 v27, v26, v26
	v_mul_f32_e32 v29, v28, v28
	v_mul_f32_e32 v31, v30, v30
	v_mul_f32_e32 v33, v32, v32
	v_mul_f32_e32 v35, v34, v34
	v_pk_add_f32 v[16:17], v[16:17], v[24:25]
	v_pk_add_f32 v[14:15], v[14:15], v[26:27]
	v_pk_add_f32 v[12:13], v[12:13], v[28:29]
	v_pk_add_f32 v[10:11], v[10:11], v[30:31]
	v_pk_add_f32 v[8:9], v[8:9], v[32:33]
	v_pk_add_f32 v[6:7], v[6:7], v[34:35]
	v_lshlrev_b32_e32 v24, 16, v39
	v_and_b32_e32 v26, 0xffff0000, v39
	v_mul_f32_e32 v25, v24, v24
	v_mul_f32_e32 v27, v26, v26
	v_pk_add_f32 v[4:5], v[4:5], v[24:25]
	v_pk_add_f32 v[2:3], v[2:3], v[26:27]
	s_waitcnt vmcnt(14)
	v_lshlrev_b32_e32 v24, 16, v40
	v_and_b32_e32 v26, 0xffff0000, v40
	v_lshlrev_b32_e32 v28, 16, v41
	v_and_b32_e32 v30, 0xffff0000, v41
	v_lshlrev_b32_e32 v32, 16, v42
	v_and_b32_e32 v34, 0xffff0000, v42
	v_mul_f32_e32 v25, v24, v24
	v_mul_f32_e32 v27, v26, v26
	v_mul_f32_e32 v29, v28, v28
	v_mul_f32_e32 v31, v30, v30
	v_mul_f32_e32 v33, v32, v32
	v_mul_f32_e32 v35, v34, v34
	v_pk_add_f32 v[16:17], v[16:17], v[24:25]
	v_pk_add_f32 v[14:15], v[14:15], v[26:27]
	v_pk_add_f32 v[12:13], v[12:13], v[28:29]
	v_pk_add_f32 v[10:11], v[10:11], v[30:31]
	v_pk_add_f32 v[8:9], v[8:9], v[32:33]
	v_pk_add_f32 v[6:7], v[6:7], v[34:35]
	v_lshlrev_b32_e32 v24, 16, v43
	v_and_b32_e32 v26, 0xffff0000, v43
	v_mul_f32_e32 v25, v24, v24
	v_mul_f32_e32 v27, v26, v26
	v_pk_add_f32 v[4:5], v[4:5], v[24:25]
	v_pk_add_f32 v[2:3], v[2:3], v[26:27]
	s_waitcnt vmcnt(13)
	v_lshlrev_b32_e32 v24, 16, v44
	v_and_b32_e32 v26, 0xffff0000, v44
	v_lshlrev_b32_e32 v28, 16, v45
	v_and_b32_e32 v30, 0xffff0000, v45
	v_lshlrev_b32_e32 v32, 16, v46
	v_and_b32_e32 v34, 0xffff0000, v46
	v_mul_f32_e32 v25, v24, v24
	v_mul_f32_e32 v27, v26, v26
	v_mul_f32_e32 v29, v28, v28
	v_mul_f32_e32 v31, v30, v30
	v_mul_f32_e32 v33, v32, v32
	v_mul_f32_e32 v35, v34, v34
	v_pk_add_f32 v[16:17], v[16:17], v[24:25]
	v_pk_add_f32 v[14:15], v[14:15], v[26:27]
	v_pk_add_f32 v[12:13], v[12:13], v[28:29]
	v_pk_add_f32 v[10:11], v[10:11], v[30:31]
	v_pk_add_f32 v[8:9], v[8:9], v[32:33]
	v_pk_add_f32 v[6:7], v[6:7], v[34:35]
	v_lshlrev_b32_e32 v24, 16, v47
	v_and_b32_e32 v26, 0xffff0000, v47
	v_mul_f32_e32 v25, v24, v24
	v_mul_f32_e32 v27, v26, v26
	v_pk_add_f32 v[4:5], v[4:5], v[24:25]
	v_pk_add_f32 v[2:3], v[2:3], v[26:27]
	s_waitcnt vmcnt(12)
	v_lshlrev_b32_e32 v24, 16, v48
	v_and_b32_e32 v26, 0xffff0000, v48
	v_lshlrev_b32_e32 v28, 16, v49
	v_and_b32_e32 v30, 0xffff0000, v49
	v_lshlrev_b32_e32 v32, 16, v50
	v_and_b32_e32 v34, 0xffff0000, v50
	v_mul_f32_e32 v25, v24, v24
	v_mul_f32_e32 v27, v26, v26
	v_mul_f32_e32 v29, v28, v28
	v_mul_f32_e32 v31, v30, v30
	v_mul_f32_e32 v33, v32, v32
	v_mul_f32_e32 v35, v34, v34
	v_pk_add_f32 v[16:17], v[16:17], v[24:25]
	v_pk_add_f32 v[14:15], v[14:15], v[26:27]
	v_pk_add_f32 v[12:13], v[12:13], v[28:29]
	v_pk_add_f32 v[10:11], v[10:11], v[30:31]
	v_pk_add_f32 v[8:9], v[8:9], v[32:33]
	v_pk_add_f32 v[6:7], v[6:7], v[34:35]
	v_lshlrev_b32_e32 v24, 16, v51
	v_and_b32_e32 v26, 0xffff0000, v51
	v_mul_f32_e32 v25, v24, v24
	v_mul_f32_e32 v27, v26, v26
	v_pk_add_f32 v[4:5], v[4:5], v[24:25]
	v_pk_add_f32 v[2:3], v[2:3], v[26:27]
	s_waitcnt vmcnt(11)
	v_lshlrev_b32_e32 v24, 16, v52
	v_and_b32_e32 v26, 0xffff0000, v52
	v_lshlrev_b32_e32 v28, 16, v53
	v_and_b32_e32 v30, 0xffff0000, v53
	v_lshlrev_b32_e32 v32, 16, v54
	v_and_b32_e32 v34, 0xffff0000, v54
	v_mul_f32_e32 v25, v24, v24
	v_mul_f32_e32 v27, v26, v26
	v_mul_f32_e32 v29, v28, v28
	v_mul_f32_e32 v31, v30, v30
	v_mul_f32_e32 v33, v32, v32
	v_mul_f32_e32 v35, v34, v34
	v_pk_add_f32 v[16:17], v[16:17], v[24:25]
	v_pk_add_f32 v[14:15], v[14:15], v[26:27]
	v_pk_add_f32 v[12:13], v[12:13], v[28:29]
	v_pk_add_f32 v[10:11], v[10:11], v[30:31]
	v_pk_add_f32 v[8:9], v[8:9], v[32:33]
	v_pk_add_f32 v[6:7], v[6:7], v[34:35]
	v_lshlrev_b32_e32 v24, 16, v55
	v_and_b32_e32 v26, 0xffff0000, v55
	v_mul_f32_e32 v25, v24, v24
	v_mul_f32_e32 v27, v26, v26
	v_pk_add_f32 v[4:5], v[4:5], v[24:25]
	v_pk_add_f32 v[2:3], v[2:3], v[26:27]
	s_waitcnt vmcnt(10)
; __device__ __forceinline__ void unpack8(const u32x4 w, float* v) { v[0] = bflo(w.x); v[1] = bfhi(w.x); v[2] = bflo(w.y); v[3] = bfhi(w.y); v[4] = bflo(w.z); v[5] = bfhi(w.z); v[6] = bflo(w.w); v[7] = bfhi(w.w); }
; __device__ __forceinline__ void sgu_unit(const bf16_t* __restrict__ VCT, const bf16_t* __restrict__ U, const bf16_t* __restrict__ GC, bf16_t* __restrict__ OC, ...
;     ...
;         const int tl = lane & 15, cq = lane >> 4;
;         const bf16_t* p = VCT + (size_t)(w * 128 + cq) * PT + tok0 + 8 * tl;
;         float sm[8], sq[8];
; #pragma unroll
;         for (int e = 0; e < 8; ++e) { sm[e] = 0.f; sq[e] = 0.f; }
; #pragma unroll 8
;         for (int c4 = 0; c4 < 32; ++c4) { float v[8]; unpack8(*(const u32x4*)(p + (size_t)(c4 * 4) * PT), v);
; #pragma unroll
;             for (int e = 0; e < 8; ++e) { sm[e] += v[e]; sq[e] += v[e] * v[e]; } }
	v_lshlrev_b32_e32 v24, 16, v56
	v_and_b32_e32 v26, 0xffff0000, v56
	v_lshlrev_b32_e32 v28, 16, v57
	v_and_b32_e32 v30, 0xffff0000, v57
	v_lshlrev_b32_e32 v32, 16, v58
	v_and_b32_e32 v34, 0xffff0000, v58
	v_mul_f32_e32 v25, v24, v24
	v_mul_f32_e32 v27, v26, v26
	v_mul_f32_e32 v29, v28, v28
	v_mul_f32_e32 v31, v30, v30
	v_mul_f32_e32 v33, v32, v32
	v_mul_f32_e32 v35, v34, v34
	v_pk_add_f32 v[16:17], v[16:17], v[24:25]
	v_pk_add_f32 v[14:15], v[14:15], v[26:27]
	v_pk_add_f32 v[12:13], v[12:13], v[28:29]
	v_pk_add_f32 v[10:11], v[10:11], v[30:31]
	v_pk_add_f32 v[8:9], v[8:9], v[32:33]
	v_pk_add_f32 v[6:7], v[6:7], v[34:35]
	v_lshlrev_b32_e32 v24, 16, v59
	v_and_b32_e32 v26, 0xffff0000, v59
	v_mul_f32_e32 v25, v24, v24
	v_mul_f32_e32 v27, v26, v26
	v_pk_add_f32 v[4:5], v[4:5], v[24:25]
	v_pk_add_f32 v[2:3], v[2:3], v[26:27]
	s_waitcnt vmcnt(9)
	v_lshlrev_b32_e32 v24, 16, v60
	v_and_b32_e32 v26, 0xffff0000, v60
	v_lshlrev_b32_e32 v28, 16, v61
	v_and_b32_e32 v30, 0xffff0000, v61
	v_lshlrev_b32_e32 v32, 16, v62
	v_and_b32_e32 v34, 0xffff0000, v62
	v_mul_f32_e32 v25, v24, v24
	v_mul_f32_e32 v27, v26, v26
	v_mul_f32_e32 v29, v28, v28
	v_mul_f32_e32 v31, v30, v30
	v_mul_f32_e32 v33, v32, v32
	v_mul_f32_e32 v35, v34, v34
	v_pk_add_f32 v[16:17], v[16:17], v[24:25]
	v_pk_add_f32 v[14:15], v[14:15], v[26:27]
	v_pk_add_f32 v[12:13], v[12:13], v[28:29]
	v_pk_add_f32 v[10:11], v[10:11], v[30:31]
	v_pk_add_f32 v[8:9], v[8:9], v[32:33]
	v_pk_add_f32 v[6:7], v[6:7], v[34:35]
	v_lshlrev_b32_e32 v24, 16, v63
	v_and_b32_e32 v26, 0xffff0000, v63
	v_mul_f32_e32 v25, v24, v24
	v_mul_f32_e32 v27, v26, v26
	v_pk_add_f32 v[4:5], v[4:5], v[24:25]
	v_pk_add_f32 v[2:3], v[2:3], v[26:27]
	s_waitcnt vmcnt(8)
	v_lshlrev_b32_e32 v24, 16, v64
	v_and_b32_e32 v26, 0xffff0000, v64
	v_lshlrev_b32_e32 v28, 16, v65
	v_and_b32_e32 v30, 0xffff0000, v65
	v_lshlrev_b32_e32 v32, 16, v66
	v_and_b32_e32 v34, 0xffff0000, v66
	v_mul_f32_e32 v25, v24, v24
	v_mul_f32_e32 v27, v26, v26
	v_mul_f32_e32 v29, v28, v28
	v_mul_f32_e32 v31, v30, v30
	v_mul_f32_e32 v33, v32, v32
	v_mul_f32_e32 v35, v34, v34
	v_pk_add_f32 v[16:17], v[16:17], v[24:25]
	v_pk_add_f32 v[14:15], v[14:15], v[26:27]
	v_pk_add_f32 v[12:13], v[12:13], v[28:29]
	v_pk_add_f32 v[10:11], v[10:11], v[30:31]
	v_pk_add_f32 v[8:9], v[8:9], v[32:33]
	v_pk_add_f32 v[6:7], v[6:7], v[34:35]
	v_lshlrev_b32_e32 v24, 16, v67
	v_and_b32_e32 v26, 0xffff0000, v67
	v_mul_f32_e32 v25, v24, v24
	v_mul_f32_e32 v27, v26, v26
	v_pk_add_f32 v[4:5], v[4:5], v[24:25]
	v_pk_add_f32 v[2:3], v[2:3], v[26:27]
	s_waitcnt vmcnt(7)
	v_lshlrev_b32_e32 v24, 16, v68
	v_and_b32_e32 v26, 0xffff0000, v68
	v_lshlrev_b32_e32 v28, 16, v69
	v_and_b32_e32 v30, 0xffff0000, v69
	v_lshlrev_b32_e32 v32, 16, v70
	v_and_b32_e32 v34, 0xffff0000, v70
	v_mul_f32_e32 v25, v24, v24
	v_mul_f32_e32 v27, v26, v26
	v_mul_f32_e32 v29, v28, v28
	v_mul_f32_e32 v31, v30, v30
	v_mul_f32_e32 v33, v32, v32
	v_mul_f32_e32 v35, v34, v34
	v_pk_add_f32 v[16:17], v[16:17], v[24:25]
	v_pk_add_f32 v[14:15], v[14:15], v[26:27]
	v_pk_add_f32 v[12:13], v[12:13], v[28:29]
	v_pk_add_f32 v[10:11], v[10:11], v[30:31]
	v_pk_add_f32 v[8:9], v[8:9], v[32:33]
	v_pk_add_f32 v[6:7], v[6:7], v[34:35]
	v_lshlrev_b32_e32 v24, 16, v71
	v_and_b32_e32 v26, 0xffff0000, v71
	v_mul_f32_e32 v25, v24, v24
	v_mul_f32_e32 v27, v26, v26
	v_pk_add_f32 v[4:5], v[4:5], v[24:25]
	v_pk_add_f32 v[2:3], v[2:3], v[26:27]
	s_waitcnt vmcnt(6)
	v_lshlrev_b32_e32 v24, 16, v72
	v_and_b32_e32 v26, 0xffff0000, v72
	v_lshlrev_b32_e32 v28, 16, v73
	v_and_b32_e32 v30, 0xffff0000, v73
	v_lshlrev_b32_e32 v32, 16, v74
	v_and_b32_e32 v34, 0xffff0000, v74
	v_mul_f32_e32 v25, v24, v24
	v_mul_f32_e32 v27, v26, v26
	v_mul_f32_e32 v29, v28, v28
	v_mul_f32_e32 v31, v30, v30
	v_mul_f32_e32 v33, v32, v32
	v_mul_f32_e32 v35, v34, v34
	v_pk_add_f32 v[16:17], v[16:17], v[24:25]
	v_pk_add_f32 v[14:15], v[14:15], v[26:27]
	v_pk_add_f32 v[12:13], v[12:13], v[28:29]
	v_pk_add_f32 v[10:11], v[10:11], v[30:31]
	v_pk_add_f32 v[8:9], v[8:9], v[32:33]
	v_pk_add_f32 v[6:7], v[6:7], v[34:35]
	v_lshlrev_b32_e32 v24, 16, v75
	v_and_b32_e32 v26, 0xffff0000, v75
	v_mul_f32_e32 v25, v24, v24
	v_mul_f32_e32 v27, v26, v26
	v_pk_add_f32 v[4:5], v[4:5], v[24:25]
	v_pk_add_f32 v[2:3], v[2:3], v[26:27]
	s_waitcnt vmcnt(5)
	v_lshlrev_b32_e32 v24, 16, v76
	v_and_b32_e32 v26, 0xffff0000, v76
	v_lshlrev_b32_e32 v28, 16, v77
	v_and_b32_e32 v30, 0xffff0000, v77
	v_lshlrev_b32_e32 v32, 16, v78
	v_and_b32_e32 v34, 0xffff0000, v78
	v_mul_f32_e32 v25, v24, v24
	v_mul_f32_e32 v27, v26, v26
	v_mul_f32_e32 v29, v28, v28
	v_mul_f32_e32 v31, v30, v30
	v_mul_f32_e32 v33, v32, v32
	v_mul_f32_e32 v35, v34, v34
	v_pk_add_f32 v[16:17], v[16:17], v[24:25]
	v_pk_add_f32 v[14:15], v[14:15], v[26:27]
	v_pk_add_f32 v[12:13], v[12:13], v[28:29]
	v_pk_add_f32 v[10:11], v[10:11], v[30:31]
	v_pk_add_f32 v[8:9], v[8:9], v[32:33]
	v_pk_add_f32 v[6:7], v[6:7], v[34:35]
	v_lshlrev_b32_e32 v24, 16, v79
	v_and_b32_e32 v26, 0xffff0000, v79
	v_mul_f32_e32 v25, v24, v24
	v_mul_f32_e32 v27, v26, v26
	v_pk_add_f32 v[4:5], v[4:5], v[24:25]
	v_pk_add_f32 v[2:3], v[2:3], v[26:27]
	s_waitcnt vmcnt(4)
	v_lshlrev_b32_e32 v24, 16, v80
	v_and_b32_e32 v26, 0xffff0000, v80
	v_lshlrev_b32_e32 v28, 16, v81
	v_and_b32_e32 v30, 0xffff0000, v81
	v_lshlrev_b32_e32 v32, 16, v82
	v_and_b32_e32 v34, 0xffff0000, v82
	v_mul_f32_e32 v25, v24, v24
	v_mul_f32_e32 v27, v26, v26
	v_mul_f32_e32 v29, v28, v28
	v_mul_f32_e32 v31, v30, v30
	v_mul_f32_e32 v33, v32, v32
	v_mul_f32_e32 v35, v34, v34
	v_pk_add_f32 v[16:17], v[16:17], v[24:25]
	v_pk_add_f32 v[14:15], v[14:15], v[26:27]
	v_pk_add_f32 v[12:13], v[12:13], v[28:29]
	v_pk_add_f32 v[10:11], v[10:11], v[30:31]
	v_pk_add_f32 v[8:9], v[8:9], v[32:33]
	v_pk_add_f32 v[6:7], v[6:7], v[34:35]
	v_lshlrev_b32_e32 v24, 16, v83
	v_and_b32_e32 v26, 0xffff0000, v83
	v_mul_f32_e32 v25, v24, v24
	v_mul_f32_e32 v27, v26, v26
	v_pk_add_f32 v[4:5], v[4:5], v[24:25]
	v_pk_add_f32 v[2:3], v[2:3], v[26:27]
	s_waitcnt vmcnt(3)
; __device__ __forceinline__ void unpack8(const u32x4 w, float* v) { v[0] = bflo(w.x); v[1] = bfhi(w.x); v[2] = bflo(w.y); v[3] = bfhi(w.y); v[4] = bflo(w.z); v[5] = bfhi(w.z); v[6] = bflo(w.w); v[7] = bfhi(w.w); }
; __device__ __forceinline__ void sgu_unit(const bf16_t* __restrict__ VCT, const bf16_t* __restrict__ U, const bf16_t* __restrict__ GC, bf16_t* __restrict__ OC, ...
;     ...
; #pragma unroll 8
;         for (int c4 = 0; c4 < 32; ++c4) { float v[8]; unpack8(*(const u32x4*)(p + (size_t)(c4 * 4) * PT), v);
; #pragma unroll
;             for (int e = 0; e < 8; ++e) { sm[e] += v[e]; sq[e] += v[e] * v[e]; } }
; #pragma unroll
;         for (int e = 0; e < 8; ++e) { sm[e] += __shfl_xor(sm[e], 16); sm[e] += __shfl_xor(sm[e], 32); sq[e] += __shfl_xor(sq[e], 16); sq[e] += __shfl_xor(sq[e], 32); }
;         if (cq == 0) {
; #pragma unroll
;             for (int e = 0; e < 8; ++e) { part[(w * 128 + 8 * tl + e) * 2 + 0] = sm[e]; part[(w * 128 + 8 * tl + e) * 2 + 1] = sq[e]; }
;         }
	v_lshlrev_b32_e32 v24, 16, v84
	v_and_b32_e32 v26, 0xffff0000, v84
	v_lshlrev_b32_e32 v28, 16, v85
	v_and_b32_e32 v30, 0xffff0000, v85
	v_lshlrev_b32_e32 v32, 16, v86
	v_and_b32_e32 v34, 0xffff0000, v86
	v_mul_f32_e32 v25, v24, v24
	v_mul_f32_e32 v27, v26, v26
	v_mul_f32_e32 v29, v28, v28
	v_mul_f32_e32 v31, v30, v30
	v_mul_f32_e32 v33, v32, v32
	v_mul_f32_e32 v35, v34, v34
	v_pk_add_f32 v[16:17], v[16:17], v[24:25]
	v_pk_add_f32 v[14:15], v[14:15], v[26:27]
	v_pk_add_f32 v[12:13], v[12:13], v[28:29]
	v_pk_add_f32 v[10:11], v[10:11], v[30:31]
	v_pk_add_f32 v[8:9], v[8:9], v[32:33]
	v_pk_add_f32 v[6:7], v[6:7], v[34:35]
	v_lshlrev_b32_e32 v24, 16, v87
	v_and_b32_e32 v26, 0xffff0000, v87
	v_mul_f32_e32 v25, v24, v24
	v_mul_f32_e32 v27, v26, v26
	v_pk_add_f32 v[4:5], v[4:5], v[24:25]
	v_pk_add_f32 v[2:3], v[2:3], v[26:27]
	s_waitcnt vmcnt(2)
	v_lshlrev_b32_e32 v24, 16, v88
	v_and_b32_e32 v26, 0xffff0000, v88
	v_lshlrev_b32_e32 v28, 16, v89
	v_and_b32_e32 v30, 0xffff0000, v89
	v_lshlrev_b32_e32 v32, 16, v90
	v_and_b32_e32 v34, 0xffff0000, v90
	v_mul_f32_e32 v25, v24, v24
	v_mul_f32_e32 v27, v26, v26
	v_mul_f32_e32 v29, v28, v28
	v_mul_f32_e32 v31, v30, v30
	v_mul_f32_e32 v33, v32, v32
	v_mul_f32_e32 v35, v34, v34
	v_pk_add_f32 v[16:17], v[16:17], v[24:25]
	v_pk_add_f32 v[14:15], v[14:15], v[26:27]
	v_pk_add_f32 v[12:13], v[12:13], v[28:29]
	v_pk_add_f32 v[10:11], v[10:11], v[30:31]
	v_pk_add_f32 v[8:9], v[8:9], v[32:33]
	v_pk_add_f32 v[6:7], v[6:7], v[34:35]
	v_lshlrev_b32_e32 v24, 16, v91
	v_and_b32_e32 v26, 0xffff0000, v91
	v_mul_f32_e32 v25, v24, v24
	v_mul_f32_e32 v27, v26, v26
	v_pk_add_f32 v[4:5], v[4:5], v[24:25]
	v_pk_add_f32 v[2:3], v[2:3], v[26:27]
	s_waitcnt vmcnt(1)
	v_lshlrev_b32_e32 v24, 16, v92
	v_and_b32_e32 v26, 0xffff0000, v92
	v_lshlrev_b32_e32 v28, 16, v93
	v_and_b32_e32 v30, 0xffff0000, v93
	v_lshlrev_b32_e32 v32, 16, v94
	v_and_b32_e32 v34, 0xffff0000, v94
	v_mul_f32_e32 v25, v24, v24
	v_mul_f32_e32 v27, v26, v26
	v_mul_f32_e32 v29, v28, v28
	v_mul_f32_e32 v31, v30, v30
	v_mul_f32_e32 v33, v32, v32
	v_mul_f32_e32 v35, v34, v34
	v_pk_add_f32 v[16:17], v[16:17], v[24:25]
	v_pk_add_f32 v[14:15], v[14:15], v[26:27]
	v_pk_add_f32 v[12:13], v[12:13], v[28:29]
	v_pk_add_f32 v[10:11], v[10:11], v[30:31]
	v_pk_add_f32 v[8:9], v[8:9], v[32:33]
	v_pk_add_f32 v[6:7], v[6:7], v[34:35]
	v_lshlrev_b32_e32 v24, 16, v95
	v_and_b32_e32 v26, 0xffff0000, v95
	v_mul_f32_e32 v25, v24, v24
	v_mul_f32_e32 v27, v26, v26
	v_pk_add_f32 v[4:5], v[4:5], v[24:25]
	v_pk_add_f32 v[2:3], v[2:3], v[26:27]
	s_waitcnt vmcnt(0)
	v_lshlrev_b32_e32 v24, 16, v96
	v_and_b32_e32 v26, 0xffff0000, v96
	v_lshlrev_b32_e32 v28, 16, v97
	v_and_b32_e32 v30, 0xffff0000, v97
	v_lshlrev_b32_e32 v32, 16, v98
	v_and_b32_e32 v34, 0xffff0000, v98
	v_mul_f32_e32 v25, v24, v24
	v_mul_f32_e32 v27, v26, v26
	v_mul_f32_e32 v29, v28, v28
	v_mul_f32_e32 v31, v30, v30
	v_mul_f32_e32 v33, v32, v32
	v_mul_f32_e32 v35, v34, v34
	v_pk_add_f32 v[16:17], v[16:17], v[24:25]
	v_pk_add_f32 v[14:15], v[14:15], v[26:27]
	v_pk_add_f32 v[12:13], v[12:13], v[28:29]
	v_pk_add_f32 v[10:11], v[10:11], v[30:31]
	v_pk_add_f32 v[8:9], v[8:9], v[32:33]
	v_pk_add_f32 v[6:7], v[6:7], v[34:35]
	v_lshlrev_b32_e32 v24, 16, v99
	v_and_b32_e32 v26, 0xffff0000, v99
	v_mul_f32_e32 v25, v24, v24
	v_mul_f32_e32 v27, v26, v26
	v_pk_add_f32 v[4:5], v[4:5], v[24:25]
	v_pk_add_f32 v[2:3], v[2:3], v[26:27]
	s_add_u32 s8, s8, 0x202000
	s_addc_u32 s9, s9, 0
	s_cmp_eq_u32 s8, 0x404000
	s_cbranch_scc0 .LBB0_222
	v_and_b32_e32 v1, 64, v182
	v_xor_b32_e32 v0, 16, v182
	v_add_u32_e32 v18, 64, v1
	v_cmp_lt_i32_e32 vcc, v0, v18
	v_xor_b32_e32 v19, 32, v182
	s_nop 0
	v_cndmask_b32_e32 v0, v182, v0, vcc
	v_cmp_lt_i32_e32 vcc, v19, v18
	v_lshlrev_b32_e32 v31, 2, v0
	ds_bpermute_b32 v0, v31, v16
	v_cndmask_b32_e32 v20, v182, v19, vcc
	ds_bpermute_b32 v1, v31, v17
	ds_bpermute_b32 v18, v31, v14
	ds_bpermute_b32 v19, v31, v15
	v_lshlrev_b32_e32 v32, 2, v20
	ds_bpermute_b32 v20, v31, v12
	ds_bpermute_b32 v21, v31, v13
	ds_bpermute_b32 v22, v31, v10
	ds_bpermute_b32 v23, v31, v11
	ds_bpermute_b32 v24, v31, v8
	ds_bpermute_b32 v25, v31, v9
	ds_bpermute_b32 v26, v31, v6
	ds_bpermute_b32 v27, v31, v7
	ds_bpermute_b32 v28, v31, v4
	ds_bpermute_b32 v29, v31, v5
	ds_bpermute_b32 v30, v31, v2
	ds_bpermute_b32 v31, v31, v3
	s_waitcnt lgkmcnt(14)
	v_pk_add_f32 v[0:1], v[16:17], v[0:1]
	s_waitcnt lgkmcnt(12)
	v_pk_add_f32 v[14:15], v[14:15], v[18:19]
	s_waitcnt lgkmcnt(10)
	v_pk_add_f32 v[12:13], v[12:13], v[20:21]
	s_waitcnt lgkmcnt(8)
	v_pk_add_f32 v[10:11], v[10:11], v[22:23]
	s_waitcnt lgkmcnt(6)
	v_pk_add_f32 v[8:9], v[8:9], v[24:25]
	s_waitcnt lgkmcnt(4)
	v_pk_add_f32 v[6:7], v[6:7], v[26:27]
	s_waitcnt lgkmcnt(2)
	v_pk_add_f32 v[4:5], v[4:5], v[28:29]
	s_waitcnt lgkmcnt(0)
	v_pk_add_f32 v[2:3], v[2:3], v[30:31]
	ds_bpermute_b32 v16, v32, v0
	ds_bpermute_b32 v17, v32, v1
	ds_bpermute_b32 v18, v32, v14
	ds_bpermute_b32 v19, v32, v15
	ds_bpermute_b32 v20, v32, v12
	ds_bpermute_b32 v21, v32, v13
	ds_bpermute_b32 v22, v32, v10
	ds_bpermute_b32 v23, v32, v11
	ds_bpermute_b32 v24, v32, v8
	ds_bpermute_b32 v25, v32, v9
	ds_bpermute_b32 v26, v32, v6
	ds_bpermute_b32 v27, v32, v7
	ds_bpermute_b32 v28, v32, v4
	ds_bpermute_b32 v29, v32, v5
	ds_bpermute_b32 v30, v32, v2
	ds_bpermute_b32 v31, v32, v3
	s_and_saveexec_b64 s[8:9], s[2:3]
	s_cbranch_execz .LBB0_225
	v_or_b32_e32 v32, s28, v155
	v_lshl_add_u32 v32, v32, 3, 0
	s_waitcnt lgkmcnt(14)
	v_pk_add_f32 v[16:17], v[0:1], v[16:17]
	s_waitcnt lgkmcnt(12)
	v_pk_add_f32 v[18:19], v[14:15], v[18:19]
	s_waitcnt lgkmcnt(10)
	v_pk_add_f32 v[12:13], v[12:13], v[20:21]
	s_waitcnt lgkmcnt(8)
	v_pk_add_f32 v[14:15], v[10:11], v[22:23]
	s_waitcnt lgkmcnt(6)
	v_pk_add_f32 v[8:9], v[8:9], v[24:25]
	s_waitcnt lgkmcnt(4)
	v_pk_add_f32 v[10:11], v[6:7], v[26:27]
	s_waitcnt lgkmcnt(2)
	v_pk_add_f32 v[0:1], v[4:5], v[28:29]
	s_waitcnt lgkmcnt(0)
	v_pk_add_f32 v[2:3], v[2:3], v[30:31]
	ds_write_b128 v32, v[16:19]
	ds_write_b128 v32, v[12:15] offset:16
	ds_write_b128 v32, v[8:11] offset:32
	ds_write_b128 v32, v[0:3] offset:48
